# v14 plus prompt-unit id remap: the eight query blocks of one batch-head are dequeued consecutively (shared K/V in flight together)
# baseline (speedup 1.0000x reference)
.LBB0_875:
	s_andn2_b64 vcc, exec, s[8:9]
	s_cbranch_vccnz .LBB0_877
	s_and_b32 s99, s10, 7
	s_lshl_b32 s99, s99, 7
	s_lshr_b32 s10, s10, 3
	s_or_b32 s10, s10, s99
	s_ashr_i32 s8, s10, 7
	s_sub_i32 s16, 7, s8
	s_lshl_b32 s8, s10, 8
	s_and_b32 s14, s8, 0x7800
	s_and_b32 s8, s10, 0x78
	s_add_i32 s8, s16, s8
	s_and_b32 s15, s10, 7
	s_lshl_b32 s8, s8, 8
	s_branch .LBB0_878
